# one L1 invalidate per CU per barrier (last arriver on the CU, keyed by HW_ID) plus a 4-byte placement shift of all later code
# speedup vs baseline: 1.0113x; 1.0107x over previous
; #define LAS __attribute__((address_space(3)))
; __global__ void __launch_bounds__(NTHR, 2) mega(P p, int ph_lo, int ph_hi) {
;     ...
;   __shared__ uint4 xb_words;
;   if (threadIdx.x == 0) xb_words = make_uint4(0u, 0u, 0u, 0u);
;   __syncthreads();
;   XcdBarrier xb; xb.bar = p.bar; xb.x = 0; xb.st = (volatile LAS unsigned*)&xb_words;
;   if (blockIdx.x == 0) { for (int i = threadIdx.x; i < XCD_BAR_WORDS; i += NTHR) p.bar[i] = 0u; }
.LBB0_2:
	s_or_b64 exec, exec, s[2:3]
	s_mov_b32 s2, 0
	s_nop 0
	v_writelane_b32 v229, s2, 58
	v_writelane_b32 v229, s2, 59
	v_writelane_b32 v229, s2, 60
	s_load_dwordx2 s[82:83], s[0:1], 0x898
	s_load_dwordx2 s[34:35], s[0:1], 0x230
	v_readlane_b32 s2, v230, 0
	s_cmp_lg_u32 s2, 0
	s_waitcnt lgkmcnt(0)
	s_barrier
	s_cbranch_scc0 .LBB0_4
	s_load_dwordx2 s[8:9], s[0:1], 0x890
	s_waitcnt lgkmcnt(0)
	s_cmp_ge_i32 s8, s9
	s_cbranch_scc0 .LBB0_11
	s_getpc_b64 s[98:99]

; __device__ __forceinline__ unsigned xb_ld(unsigned* p)              { return __hip_atomic_load(p, __ATOMIC_RELAXED, __HIP_MEMORY_SCOPE_AGENT); }
; __device__ __forceinline__ unsigned xb_add(unsigned* p, unsigned v) { return __hip_atomic_fetch_add(p, v, __ATOMIC_RELAXED, __HIP_MEMORY_SCOPE_AGENT); }
; __device__ __forceinline__ void xcd_barrier_complete(unsigned* bar, unsigned x, unsigned& nloc, unsigned& nx) {
;     ...
;     for (unsigned j = 0; j < 16; ++j) { const unsigned c = xb_ld(&bar[XB_XCNT(j)]); sum += c; cnt += (c > 0u) ? 1u : 0u; mine = (j == x) ? c : mine; }
;     if (sum == G) break;
;     __builtin_amdgcn_s_sleep(1);
;     if ((++sp & 255u) == 0u) { if (xb_ld(&bar[XB_TMO])) break; if (sp > XB_SPIN_CAP) { atomicAdd(&bar[XB_TMO], 1u); break; } }
;   }
;   nloc = mine > 0u ? mine : 1u; nx = cnt > 0u ? cnt : 1u;
; }
; __device__ __forceinline__ void xcd_barrier(const XcdBarrier& b) {
;   asm volatile("s_waitcnt vmcnt(0)" ::: "memory");
;   __syncthreads();
;   if (threadIdx.x == 0) {
;     unsigned* bar = b.bar;
;     __builtin_amdgcn_s_waitcnt(0);
;     unsigned nloc = b.st[0], nx = b.st[1];
;     if (nloc == 0u) { xcd_barrier_complete(bar, b.x, nloc, nx); b.st[0] = nloc; b.st[1] = nx; }
;     const unsigned old = xb_add(&bar[XB_XSUB(b.x)], 1u);
;     const unsigned gen = old / nloc;
;     if (old + 1u == (gen + 1u) * nloc) {
.LBB0_31:
	v_readlane_b32 s4, v229, 26
	s_cmp_eq_u32 s4, 0
	s_cselect_b64 vcc, -1, 0
	s_cmp_eq_u32 s4, 1
	v_cndmask_b32_e32 v16, 0, v11, vcc
	s_cselect_b64 vcc, -1, 0
	s_cmp_eq_u32 s4, 2
	v_cndmask_b32_e32 v16, v16, v0, vcc
	s_cselect_b64 vcc, -1, 0
	s_cmp_eq_u32 s4, 3
	v_cndmask_b32_e32 v16, v16, v1, vcc
	s_cselect_b64 vcc, -1, 0
	s_cmp_eq_u32 s4, 4
	v_cndmask_b32_e32 v16, v16, v2, vcc
	s_cselect_b64 vcc, -1, 0
	s_cmp_eq_u32 s4, 5
	v_cndmask_b32_e32 v16, v16, v3, vcc
	s_cselect_b64 vcc, -1, 0
	s_cmp_eq_u32 s4, 6
	v_cndmask_b32_e32 v16, v16, v4, vcc
	s_cselect_b64 vcc, -1, 0
	s_cmp_eq_u32 s4, 7
	v_cndmask_b32_e32 v16, v16, v5, vcc
	s_cselect_b64 vcc, -1, 0
	s_cmp_eq_u32 s4, 8
	v_cndmask_b32_e32 v16, v16, v6, vcc
	s_cselect_b64 vcc, -1, 0
	s_cmp_eq_u32 s4, 9
	v_cndmask_b32_e32 v16, v16, v7, vcc
	s_cselect_b64 vcc, -1, 0
	s_cmp_eq_u32 s4, 10
	v_cndmask_b32_e32 v16, v16, v8, vcc
	s_cselect_b64 vcc, -1, 0
	s_cmp_eq_u32 s4, 11
	v_cndmask_b32_e32 v16, v16, v9, vcc
	s_cselect_b64 vcc, -1, 0
	s_cmp_eq_u32 s4, 12
	v_cndmask_b32_e32 v16, v16, v10, vcc
	s_cselect_b64 vcc, -1, 0
	s_cmp_eq_u32 s4, 13
	v_cndmask_b32_e32 v16, v16, v12, vcc
	s_cselect_b64 vcc, -1, 0
	s_cmp_eq_u32 s4, 14
	v_cndmask_b32_e32 v16, v16, v13, vcc
	s_cselect_b64 vcc, -1, 0
	s_cmp_eq_u32 s4, 15
	v_cndmask_b32_e32 v16, v16, v14, vcc
	s_cselect_b64 vcc, -1, 0
	v_cndmask_b32_e32 v16, v16, v15, vcc
	v_cmp_ne_u32_e32 vcc, 0, v11
	s_nop 1
	v_cndmask_b32_e64 v11, 0, 1, vcc
	v_cmp_ne_u32_e32 vcc, 0, v0
	s_nop 1
	v_addc_co_u32_e32 v0, vcc, 0, v11, vcc
	v_cmp_ne_u32_e32 vcc, 0, v1
	s_nop 1
	v_cndmask_b32_e64 v1, 0, 1, vcc
	v_cmp_ne_u32_e32 vcc, 0, v2
	v_max_u32_e32 v2, 1, v16
	s_nop 0
	v_addc_co_u32_e32 v0, vcc, v0, v1, vcc
	v_cmp_ne_u32_e32 vcc, 0, v3
	s_nop 1
	v_cndmask_b32_e64 v1, 0, 1, vcc
	v_cmp_ne_u32_e32 vcc, 0, v4
	s_nop 1
	v_addc_co_u32_e32 v0, vcc, v0, v1, vcc
	v_cmp_ne_u32_e32 vcc, 0, v5
	s_nop 1
	v_cndmask_b32_e64 v1, 0, 1, vcc
	v_cmp_ne_u32_e32 vcc, 0, v6
	s_nop 1
	v_addc_co_u32_e32 v0, vcc, v0, v1, vcc
	v_cmp_ne_u32_e32 vcc, 0, v7
	s_nop 1
	v_cndmask_b32_e64 v1, 0, 1, vcc
	v_cmp_ne_u32_e32 vcc, 0, v8
	s_nop 1
	v_addc_co_u32_e32 v0, vcc, v0, v1, vcc
	v_cmp_ne_u32_e32 vcc, 0, v9
	s_nop 1
	v_cndmask_b32_e64 v1, 0, 1, vcc
	v_cmp_ne_u32_e32 vcc, 0, v10
	s_nop 1
	v_addc_co_u32_e32 v0, vcc, v0, v1, vcc
	v_cmp_ne_u32_e32 vcc, 0, v12
	s_nop 1
	v_cndmask_b32_e64 v1, 0, 1, vcc
	v_cmp_ne_u32_e32 vcc, 0, v13
	s_nop 1
	v_addc_co_u32_e32 v0, vcc, v0, v1, vcc
	v_cmp_ne_u32_e32 vcc, 0, v14
	s_nop 1
	v_cndmask_b32_e64 v1, 0, 1, vcc
	v_cmp_ne_u32_e32 vcc, 0, v15
	s_nop 1
	v_addc_co_u32_e32 v0, vcc, v0, v1, vcc
	v_max_u32_e32 v0, 1, v0
	ds_write_b32 v133, v2
	ds_write_b32 v137, v0
	v_readlane_b32 s12, v229, 58
	s_nop 3
	s_cmp_eq_u32 s12, 0
	s_cbranch_scc1 .Lxb_ncu0
	v_mov_b32_e32 v8, s12
	global_load_dword v8, v8, s[34:35] sc1
	s_waitcnt vmcnt(0)
	v_readfirstlane_b32 s13, v8
	s_nop 3
	s_lshr_b32 s13, s13, 16
	s_cmp_eq_u32 s13, 0
	s_cselect_b32 s12, 0, s12
	s_sub_u32 s14, s13, 1
	s_cmp_eq_u32 s13, 0
	s_cselect_b32 s14, 0, s14
	s_nop 0
	v_writelane_b32 v229, s12, 58
	v_writelane_b32 v229, s13, 59
	v_writelane_b32 v229, s14, 60
.Lxb_ncu0:
.LBB0_32:
	v_readlane_b32 s4, v229, 26
	s_lshl_b32 s4, s4, 6
	s_lshl_b64 s[8:9], s[4:5], 2
	s_add_u32 s8, s34, s8
	s_addc_u32 s9, s35, s9
	global_atomic_add v3, v198, v199, s[8:9] offset:1024 sc0
	v_readlane_b32 s12, v229, 58
	v_readlane_b32 s13, v229, 60
	s_nop 3
	v_mov_b32_e32 v8, s13
	s_cmp_eq_u32 s12, 0
	s_cbranch_scc1 .Lxb_nocu
	v_mov_b32_e32 v9, s12
	global_atomic_add v8, v9, v199, s[34:35] sc0
.Lxb_nocu:
	v_cvt_f32_u32_e32 v1, v2
	v_sub_u32_e32 v4, 0, v2
	v_rcp_iflag_f32_e32 v1, v1
	s_nop 0
	v_mul_f32_e32 v1, 0x4f7ffffe, v1
	v_cvt_u32_f32_e32 v1, v1
	v_mul_lo_u32 v4, v4, v1
	v_mul_hi_u32 v4, v1, v4
	v_add_u32_e32 v1, v1, v4
	s_waitcnt vmcnt(0)
	v_readfirstlane_b32 s14, v8
	s_nop 3
	s_and_b32 s14, s14, 0xffff
	s_cmp_lg_u32 s14, s13
	s_cbranch_scc1 .Lxb_skipinv
	buffer_inv sc1
.Lxb_skipinv:
	v_readlane_b32 s14, v229, 59
	s_nop 3
	s_add_u32 s13, s13, s14
	s_nop 0
	v_writelane_b32 v229, s13, 60
	v_mul_hi_u32 v1, v3, v1
	v_mul_lo_u32 v4, v1, v2
	v_sub_u32_e32 v4, v3, v4
	v_add_u32_e32 v5, 1, v1
	v_cmp_ge_u32_e32 vcc, v4, v2
	v_add_u32_e32 v3, 1, v3
	s_nop 0
	v_cndmask_b32_e32 v1, v1, v5, vcc
	v_sub_u32_e32 v5, v4, v2
	v_cndmask_b32_e32 v4, v4, v5, vcc
	v_add_u32_e32 v5, 1, v1
	v_cmp_ge_u32_e32 vcc, v4, v2
	s_nop 1
	v_cndmask_b32_e32 v1, v1, v5, vcc
	v_mul_lo_u32 v4, v2, v1
	v_add_u32_e32 v2, v4, v2
	v_cmp_ne_u32_e32 vcc, v3, v2
	s_and_saveexec_b64 s[10:11], vcc
	s_xor_b64 s[10:11], exec, s[10:11]
	s_cbranch_execz .LBB0_46
	s_waitcnt lgkmcnt(0)
	s_waitcnt vmcnt(0)
	global_atomic_add v198, v199, s[8:9] offset:1152
	global_load_dword v0, v200, s[8:9] offset:1024 sc1
	s_add_u32 s14, s8, 0x2400
	s_addc_u32 s15, s9, 0
	s_waitcnt vmcnt(0)
	v_cmp_eq_u32_e32 vcc, v0, v1
	s_and_saveexec_b64 s[12:13], vcc
	s_cbranch_execz .LBB0_45
	s_mov_b32 s4, 1
	s_mov_b64 s[16:17], 0
	s_branch .LBB0_36

; #define LAS __attribute__((address_space(3)))
; __device__ __forceinline__ unsigned xb_add(unsigned* p, unsigned v) { return __hip_atomic_fetch_add(p, v, __ATOMIC_RELAXED, __HIP_MEMORY_SCOPE_AGENT); }
; __device__ __forceinline__ unsigned xb_xcc_id() { return (unsigned)__builtin_amdgcn_s_getreg((3 << 11) | 20) & 0xFu; }
; __device__ __forceinline__ XcdBarrier xcd_barrier_post(unsigned* bar, volatile LAS unsigned* st) {
;   XcdBarrier b; b.bar = bar; b.x = xb_xcc_id(); b.st = st;
;   if (threadIdx.x == 0) (void)xb_add(&bar[XB_XCNT(b.x)], 1u);
;   return b;
; }
.LBB0_76:
	s_or_b64 exec, exec, s[6:7]
	s_barrier
	s_getreg_b32 s4, hwreg(HW_REG_XCC_ID, 0, 4)
	s_and_b32 s4, s4, 15
	v_writelane_b32 v229, s4, 26
	s_mov_b64 s[6:7], exec
	v_readlane_b32 s8, v230, 3
	v_readlane_b32 s9, v230, 4
	s_and_b64 s[8:9], s[6:7], s[8:9]
	s_mov_b64 exec, s[8:9]
	s_cbranch_execz .LBB0_79
	s_mov_b64 s[8:9], exec
	v_mbcnt_lo_u32_b32 v0, s8, 0
	v_mbcnt_hi_u32_b32 v0, s9, v0
	v_cmp_eq_u32_e32 vcc, 0, v0
	s_and_b64 s[10:11], exec, vcc
	s_mov_b64 exec, s[10:11]
	s_cbranch_execz .LBB0_79
	s_getreg_b32 s10, hwreg(HW_REG_HW_ID)
	v_readlane_b32 s4, v229, 26
	s_lshr_b32 s10, s10, 8
	s_and_b32 s11, s10, 0xff
	s_and_b32 s12, s11, 0x90
	s_nop 0
	s_and_b32 s13, s11, 15
	s_lshr_b32 s14, s11, 5
	s_and_b32 s14, s14, 3
	s_lshl_b32 s14, s14, 4
	s_or_b32 s13, s13, s14
	s_cmp_eq_u32 s12, 0
	s_cselect_b32 s15, 1, 0
	s_cmp_lg_u32 s13, 0
	s_cselect_b32 s14, 1, 0
	s_and_b32 s15, s15, s14
	s_cmp_lt_u32 s4, 8
	s_cselect_b32 s14, 1, 0
	s_and_b32 s15, s15, s14
	s_add_u32 s14, s4, 8
	s_lshl_b32 s14, s14, 6
	s_add_u32 s14, s14, 0x900
	s_add_u32 s14, s14, s13
	s_lshl_b32 s14, s14, 2
	s_cmp_lg_u32 s15, 0
	s_cselect_b32 s14, s14, 0
	s_nop 0
	v_writelane_b32 v229, s14, 58
	s_cbranch_scc0 .Lxb_noreg
	v_mov_b32_e32 v2, s14
	v_mov_b32_e32 v4, 0x10000
	global_atomic_add v3, v2, v4, s[34:35] sc0
	s_waitcnt vmcnt(0)
.Lxb_noreg:
	v_readlane_b32 s4, v229, 26
	s_lshl_b32 s4, s4, 8
	s_bcnt1_i32_b64 s8, s[8:9]
	v_mov_b32_e32 v0, s4
	v_mov_b32_e32 v1, s8
	global_atomic_add v0, v1, s[34:35] offset:1024
